# P0: forget-gate bias loaded once before the row loop; the two in-loop reloads + vmcnt(0) full drains removed
# speedup vs baseline: 1.0049x; 1.0049x over previous
.LBB0_63:
	s_or_b64 exec, exec, s[6:7]
	s_cmp_lt_i32 s16, 0x10400
	s_waitcnt lgkmcnt(0)
	s_barrier
	s_cbranch_scc0 .LBB0_76
	v_and_b32_e32 v34, 32, v32
	v_cmp_eq_u32_e64 s[2:3], 0, v34
	v_and_b32_e32 v34, 16, v32
	v_cmp_eq_u32_e64 s[4:5], 0, v34
	v_and_b32_e32 v34, 8, v32
	v_cmp_eq_u32_e64 s[6:7], 0, v34
	v_and_b32_e32 v34, 7, v32
	v_cmp_eq_u32_e64 s[8:9], 0, v34
	v_mbcnt_lo_u32_b32 v34, -1, 0
	v_mbcnt_hi_u32_b32 v34, -1, v34
	v_and_b32_e32 v36, 64, v34
	v_xor_b32_e32 v35, 32, v34
	v_add_u32_e32 v36, 64, v36
	v_cmp_lt_i32_e32 vcc, v35, v36
	v_readlane_b32 s22, v255, 0
	v_lshl_add_u32 v124, v32, 4, 0
	v_cndmask_b32_e32 v35, v34, v35, vcc
	v_lshlrev_b32_e32 v164, 2, v35
	v_xor_b32_e32 v35, 16, v34
	v_cmp_lt_i32_e32 vcc, v35, v36
	v_readlane_b32 s23, v255, 1
	ds_read_b128 v[0:3], v124 offset:31744
	ds_read_b128 v[4:7], v124 offset:30720
	ds_read_b128 v[8:11], v124 offset:29696
	ds_read_b128 v[12:15], v124 offset:28672
	ds_read_b128 v[16:19], v124 offset:27648
	ds_read_b128 v[20:23], v124 offset:26624
	ds_read_b128 v[24:27], v124 offset:25600
	ds_read_b128 v[28:31], v124 offset:24576
	v_cndmask_b32_e32 v35, v34, v35, vcc
	v_lshlrev_b32_e32 v165, 2, v35
	v_xor_b32_e32 v35, 8, v34
	v_cmp_lt_i32_e32 vcc, v35, v36
	s_load_dwordx4 s[12:15], s[22:23], 0x0
	s_load_dwordx2 s[20:21], s[22:23], 0x58
	v_cndmask_b32_e32 v35, v34, v35, vcc
	v_lshlrev_b32_e32 v166, 2, v35
	v_xor_b32_e32 v35, 4, v34
	v_cmp_lt_i32_e32 vcc, v35, v36
	s_add_i32 s28, s16, s0
	v_ashrrev_i32_e32 v149, 31, v148
	v_cndmask_b32_e32 v35, v34, v35, vcc
	v_lshlrev_b32_e32 v167, 2, v35
	v_xor_b32_e32 v35, 2, v34
	v_cmp_lt_i32_e32 vcc, v35, v36
	s_ashr_i32 s29, s28, 31
	s_lshl_b32 s18, s67, 4
	v_cndmask_b32_e32 v35, v34, v35, vcc
	v_lshlrev_b32_e32 v168, 2, v35
	v_xor_b32_e32 v35, 1, v34
	v_cmp_lt_i32_e32 vcc, v35, v36
	s_waitcnt lgkmcnt(0)
	v_lshl_add_u64 v[150:151], v[148:149], 2, s[20:21]
	global_load_dword v254, v[150:151], off
	s_lshl_b64 s[20:21], s[28:29], 2
	v_ashrrev_i32_e32 v33, 31, v32
	v_cndmask_b32_e32 v34, v34, v35, vcc
	s_add_u32 s1, s20, 0x1d00000
	v_lshlrev_b32_e32 v169, 2, v34
	s_addc_u32 s24, s21, 0
	s_ashr_i32 s19, s18, 31
	s_lshl_b64 s[20:21], s[28:29], 11
	v_lshlrev_b64 v[34:35], 3, v[32:33]
	s_ashr_i32 s17, s16, 31
	s_lshl_b64 s[30:31], s[18:19], 2
	v_lshl_add_u64 v[152:153], s[20:21], 0, v[34:35]
	s_lshl_b64 s[40:41], s[18:19], 11
	s_lshl_b64 s[20:21], s[16:17], 2
	s_add_u32 s25, s20, 0x1d00000
	v_cmp_eq_u32_e64 s[10:11], 0, v32
	s_addc_u32 s26, s21, 0
	s_lshl_b64 s[20:21], s[16:17], 11
	v_lshlrev_b64 v[156:157], 4, v[32:33]
	v_lshl_add_u64 v[154:155], s[20:21], 0, v[34:35]
	ds_read_b128 v[32:35], v124 offset:23552
	ds_read_b128 v[36:39], v124 offset:22528
	ds_read_b128 v[40:43], v124 offset:21504
	ds_read_b128 v[44:47], v124 offset:20480
	ds_read_b128 v[48:51], v124 offset:19456
	ds_read_b128 v[52:55], v124 offset:18432
	ds_read_b128 v[56:59], v124 offset:17408
	ds_read_b128 v[60:63], v124 offset:16384
	ds_read_b128 v[64:67], v124 offset:15360
	ds_read_b128 v[68:71], v124 offset:14336
	ds_read_b128 v[72:75], v124 offset:13312
	ds_read_b128 v[76:79], v124 offset:12288
	ds_read_b128 v[80:83], v124 offset:11264
	ds_read_b128 v[84:87], v124 offset:10240
	ds_read_b128 v[88:91], v124 offset:9216
	ds_read_b128 v[92:95], v124 offset:8192
	ds_read_b128 v[96:99], v124 offset:7168
	ds_read_b128 v[100:103], v124 offset:6144
	ds_read_b128 v[104:107], v124 offset:5120
	ds_read_b128 v[108:111], v124 offset:4096
	ds_read_b128 v[112:115], v124 offset:3072
	ds_read_b128 v[116:119], v124 offset:2048
	ds_read_b128 v[120:123], v124 offset:1024
	ds_read_b128 v[124:127], v124
	s_load_dwordx2 s[22:23], s[22:23], 0xc8
	s_mov_b64 s[42:43], 0
	s_mov_b32 s27, 0x2800000
	v_mov_b32_e32 v170, 0x358637bd
	s_mov_b32 s33, 0x800000
	s_mov_b32 s34, 0xbfb8aa3b
	s_mov_b32 s35, 0xb2a5705f
	s_mov_b32 s36, 0x42ce8ed0
	s_mov_b32 s37, 0xc2b17218
	s_mov_b32 s38, 0x7f800000
	s_mov_b32 s39, 0x3f2aaaab
	v_mov_b32_e32 v171, 0x3ecc95a3
	s_mov_b32 s50, 0x3f317218
	s_mov_b32 s51, 0x33800000
	s_mov_b32 s52, 0x24400000
	v_mov_b32_e32 v172, 0
	v_mov_b32_e32 v173, 0x7f800000
	v_mov_b32_e32 v158, 0x3f317218
	s_mov_b32 s53, s16
	s_branch .LBB0_67

.LBB0_67:
	s_add_i32 s46, s53, 0xffff0000
	s_add_u32 s47, s16, s42
	s_addc_u32 s48, s17, s43
	s_cmp_lt_i32 s53, 0x10000
	s_cselect_b64 s[44:45], -1, 0
	s_and_b64 s[20:21], s[44:45], exec
	s_cselect_b32 s21, s48, 0
	s_cselect_b32 s20, s47, s46
	s_cselect_b32 s48, s13, s15
	s_cselect_b32 s49, s12, s14
	s_lshl_b64 s[46:47], s[20:21], 12
	s_add_u32 s46, s49, s46
	s_addc_u32 s47, s48, s47
	s_waitcnt vmcnt(6)
	v_lshl_add_u64 v[136:137], s[46:47], 0, v[156:157]
	s_waitcnt lgkmcnt(0)
	global_load_dwordx4 v[132:135], v[136:137], off offset:2048 nt
	global_load_dwordx4 v[128:131], v[136:137], off offset:3072 nt
	global_load_dwordx4 v[138:141], v[136:137], off offset:1024 nt
	global_load_dwordx4 v[144:147], v[136:137], off nt
	s_add_i32 s54, s0, s53
	s_cmp_lt_i32 s54, 0x10400
	s_cselect_b64 s[46:47], -1, 0
	s_and_b64 s[48:49], s[46:47], exec
	s_cselect_b32 s48, s54, s53
	s_ashr_i32 s49, s48, 31
	s_add_i32 s55, s48, 0xffff0000
	s_cmp_lt_i32 s48, 0x10000
	s_cselect_b32 s49, s49, 0
	s_cselect_b32 s48, s48, s55
	s_cselect_b32 s55, s13, s15
	s_cselect_b32 s56, s12, s14
	s_lshl_b64 s[48:49], s[48:49], 12
	s_add_u32 s48, s56, s48
	s_addc_u32 s49, s55, s49
	s_waitcnt vmcnt(3)
	v_mul_f32_e32 v142, v135, v135
	s_waitcnt vmcnt(2) lgkmcnt(0)
	v_mul_f32_e32 v203, v113, v129
	v_mul_f32_e32 v204, v115, v131
	v_mul_f32_e32 v205, v97, v129
	v_mul_f32_e32 v206, v99, v131
	v_mul_f32_e32 v207, v81, v129
	v_mul_f32_e32 v208, v83, v131
	v_mul_f32_e32 v209, v65, v129
	v_mul_f32_e32 v210, v67, v131
	v_mul_f32_e32 v211, v49, v129
	v_mul_f32_e32 v212, v51, v131
	v_mul_f32_e32 v213, v33, v129
	v_mul_f32_e32 v214, v35, v131
	v_mul_f32_e32 v215, v17, v129
	v_mul_f32_e32 v216, v19, v131
	v_mul_f32_e32 v217, v1, v129
	v_mul_f32_e32 v218, v3, v131
	v_pk_fma_f32 v[176:177], v[134:135], v[134:135], v[142:143] op_sel_hi:[1,1,0]
	v_mul_f32_e32 v136, v133, v133
	v_mul_f32_e32 v159, v117, v133
	v_mul_f32_e32 v189, v101, v133
	v_mul_f32_e32 v191, v85, v133
	v_mul_f32_e32 v193, v69, v133
	v_mul_f32_e32 v195, v53, v133
	v_mul_f32_e32 v197, v37, v133
	v_mul_f32_e32 v199, v21, v133
	v_mul_f32_e32 v201, v5, v133
	v_cvt_pk_bf16_f32 v162, v128, v129
	v_cvt_pk_bf16_f32 v163, v130, v131
	v_mul_f32_e32 v219, v128, v128
	v_mul_f32_e32 v220, v129, v129
	v_mul_f32_e32 v221, v130, v130
	v_fmac_f32_e32 v203, v112, v128
	v_fmac_f32_e32 v204, v114, v130
	v_fmac_f32_e32 v205, v96, v128
	v_fmac_f32_e32 v206, v98, v130
	v_fmac_f32_e32 v207, v80, v128
	v_fmac_f32_e32 v208, v82, v130
	v_fmac_f32_e32 v209, v64, v128
	v_fmac_f32_e32 v210, v66, v130
	v_fmac_f32_e32 v211, v48, v128
	v_fmac_f32_e32 v212, v50, v130
	v_fmac_f32_e32 v213, v32, v128
	v_fmac_f32_e32 v214, v34, v130
	v_fmac_f32_e32 v215, v16, v128
	v_fmac_f32_e32 v216, v18, v130
	v_fmac_f32_e32 v217, v0, v128
	v_fmac_f32_e32 v218, v2, v130
	v_mul_f32_e32 v177, v131, v131
	s_waitcnt vmcnt(1)
	v_pk_mul_f32 v[128:129], v[140:141], v[140:141]
	v_pk_mul_f32 v[130:131], v[138:139], v[138:139]
	v_cvt_pk_bf16_f32 v160, v132, v133
	v_mul_f32_e32 v188, v119, v135
	v_mul_f32_e32 v190, v103, v135
	v_mul_f32_e32 v192, v87, v135
	v_mul_f32_e32 v194, v71, v135
	v_mul_f32_e32 v196, v55, v135
	v_mul_f32_e32 v198, v39, v135
	v_mul_f32_e32 v200, v23, v135
	v_mul_f32_e32 v202, v7, v135
	v_pk_fma_f32 v[174:175], v[132:133], v[132:133], v[136:137] op_sel_hi:[1,1,0]
	v_fmac_f32_e32 v159, v116, v132
	v_fmac_f32_e32 v189, v100, v132
	v_fmac_f32_e32 v191, v84, v132
	v_fmac_f32_e32 v193, v68, v132
	v_fmac_f32_e32 v195, v52, v132
	v_fmac_f32_e32 v197, v36, v132
	v_fmac_f32_e32 v199, v20, v132
	v_fmac_f32_e32 v201, v4, v132
	v_mul_f32_e32 v222, v121, v139
	v_mul_f32_e32 v223, v123, v141
	v_mul_f32_e32 v224, v105, v139
	v_mul_f32_e32 v225, v107, v141
	v_mul_f32_e32 v226, v89, v139
	v_mul_f32_e32 v227, v91, v141
	v_mul_f32_e32 v228, v73, v139
	v_mul_f32_e32 v229, v75, v141
	v_mul_f32_e32 v230, v57, v139
	v_mul_f32_e32 v231, v59, v141
	v_mul_f32_e32 v232, v41, v139
	v_mul_f32_e32 v233, v43, v141
	v_mul_f32_e32 v234, v25, v139
	v_mul_f32_e32 v235, v27, v141
	v_mul_f32_e32 v236, v9, v139
	v_mul_f32_e32 v237, v11, v141
	v_pk_mov_b32 v[132:133], v[130:131], v[128:129] op_sel:[1,0]
	v_mov_b32_e32 v131, v129
	v_lshl_add_u64 v[128:129], s[48:49], 0, v[156:157]
	v_cvt_pk_bf16_f32 v161, v134, v135
	v_fmac_f32_e32 v188, v118, v134
	v_fmac_f32_e32 v190, v102, v134
	v_fmac_f32_e32 v192, v86, v134
	v_fmac_f32_e32 v194, v70, v134
	v_fmac_f32_e32 v196, v54, v134
	v_fmac_f32_e32 v198, v38, v134
	v_fmac_f32_e32 v200, v22, v134
	v_fmac_f32_e32 v202, v6, v134
	v_cvt_pk_bf16_f32 v178, v138, v139
	v_cvt_pk_bf16_f32 v179, v140, v141
	v_fmac_f32_e32 v222, v120, v138
	v_fmac_f32_e32 v223, v122, v140
	v_fmac_f32_e32 v224, v104, v138
	v_fmac_f32_e32 v225, v106, v140
	v_fmac_f32_e32 v226, v88, v138
	v_fmac_f32_e32 v227, v90, v140
	v_fmac_f32_e32 v228, v72, v138
	v_fmac_f32_e32 v229, v74, v140
	v_fmac_f32_e32 v230, v56, v138
	v_fmac_f32_e32 v231, v58, v140
	v_fmac_f32_e32 v232, v40, v138
	v_fmac_f32_e32 v233, v42, v140
	v_fmac_f32_e32 v234, v24, v138
	v_fmac_f32_e32 v235, v26, v140
	v_fmac_f32_e32 v236, v8, v138
	v_fmac_f32_e32 v237, v10, v140
	v_pk_add_f32 v[180:181], v[132:133], v[130:131]
	global_load_dwordx4 v[140:143], v[128:129], off nt
	global_load_dwordx4 v[136:139], v[128:129], off offset:1024 nt
	global_load_dwordx4 v[132:135], v[128:129], off offset:2048 nt
	s_nop 0
	global_load_dwordx4 v[128:131], v[128:129], off offset:3072 nt
	s_waitcnt vmcnt(4)
	v_pk_mul_f32 v[182:183], v[146:147], v[146:147]
	v_pk_mul_f32 v[184:185], v[144:145], v[144:145]
	v_mov_b32_e32 v175, v221
	v_pk_mov_b32 v[186:187], v[184:185], v[182:183] op_sel:[1,0]
	v_mov_b32_e32 v185, v183
	v_pk_add_f32 v[182:183], v[186:187], v[184:185]
	v_pk_add_f32 v[174:175], v[174:175], v[176:177]
	v_pk_add_f32 v[176:177], v[182:183], v[182:183] op_sel:[0,1] op_sel_hi:[1,0]
	v_pk_add_f32 v[180:181], v[180:181], v[180:181] op_sel:[0,1] op_sel_hi:[1,0]
	v_mul_f32_e32 v238, v125, v145
	v_mul_f32_e32 v239, v127, v147
	v_mov_b32_e32 v177, v219
	v_mov_b32_e32 v181, v220
	v_fmac_f32_e32 v238, v124, v144
	v_fmac_f32_e32 v239, v126, v146
	v_pk_add_f32 v[176:177], v[176:177], v[180:181]
	v_mul_f32_e32 v240, v109, v145
	v_pk_add_f32 v[174:175], v[176:177], v[174:175]
	v_add_f32_e32 v176, v238, v239
	v_add_f32_e32 v177, v222, v223
	v_add_f32_e32 v176, 0, v176
	v_mul_f32_e32 v241, v111, v147
	v_add_f32_e32 v176, v176, v177
	v_add_f32_e32 v159, v159, v188
	v_fmac_f32_e32 v240, v108, v144
	v_fmac_f32_e32 v241, v110, v146
	v_add_f32_e32 v159, v176, v159
	v_add_f32_e32 v176, v203, v204
	v_add_f32_e32 v159, v159, v176
	v_add_f32_e32 v176, v240, v241
	v_add_f32_e32 v177, v224, v225
	v_add_f32_e32 v176, 0, v176
	v_mul_f32_e32 v242, v93, v145
	v_mul_f32_e32 v243, v95, v147
	v_add_f32_e32 v176, v176, v177
	v_add_f32_e32 v177, v189, v190
	v_fmac_f32_e32 v242, v92, v144
	v_fmac_f32_e32 v243, v94, v146
	v_add_f32_e32 v176, v176, v177
	v_add_f32_e32 v177, v205, v206
	v_add_f32_e32 v176, v176, v177
	v_add_f32_e32 v177, v242, v243
	v_add_f32_e32 v180, v226, v227
	v_add_f32_e32 v177, 0, v177
	v_mul_f32_e32 v244, v77, v145
	v_mul_f32_e32 v245, v79, v147
	v_add_f32_e32 v177, v177, v180
	v_add_f32_e32 v180, v191, v192
	v_fmac_f32_e32 v244, v76, v144
	v_fmac_f32_e32 v245, v78, v146
	v_add_f32_e32 v177, v177, v180
	v_add_f32_e32 v180, v207, v208
	v_add_f32_e32 v177, v177, v180
	v_add_f32_e32 v180, v244, v245
	v_add_f32_e32 v181, v228, v229
	v_add_f32_e32 v180, 0, v180
	v_mul_f32_e32 v246, v61, v145
	v_mul_f32_e32 v247, v63, v147
	v_add_f32_e32 v180, v180, v181
	v_add_f32_e32 v181, v193, v194
	v_fmac_f32_e32 v246, v60, v144
	v_fmac_f32_e32 v247, v62, v146
	v_add_f32_e32 v180, v180, v181
	v_add_f32_e32 v181, v209, v210
	v_add_f32_e32 v180, v180, v181
	v_add_f32_e32 v181, v246, v247
	v_add_f32_e32 v182, v230, v231
	v_add_f32_e32 v181, 0, v181
	v_mul_f32_e32 v248, v45, v145
	v_mul_f32_e32 v249, v47, v147
	v_add_f32_e32 v181, v181, v182
	v_add_f32_e32 v182, v195, v196
	v_fmac_f32_e32 v248, v44, v144
	v_fmac_f32_e32 v249, v46, v146
	v_add_f32_e32 v181, v181, v182
	v_add_f32_e32 v182, v211, v212
	v_add_f32_e32 v181, v181, v182
	v_add_f32_e32 v182, v248, v249
	v_add_f32_e32 v183, v232, v233
	v_add_f32_e32 v182, 0, v182
	v_mul_f32_e32 v250, v29, v145
	v_mul_f32_e32 v251, v31, v147
	v_add_f32_e32 v182, v182, v183
	v_add_f32_e32 v183, v197, v198
	v_fmac_f32_e32 v250, v28, v144
	v_fmac_f32_e32 v251, v30, v146
	v_add_f32_e32 v182, v182, v183
	v_add_f32_e32 v183, v213, v214
	v_add_f32_e32 v182, v182, v183
	v_add_f32_e32 v183, v250, v251
	v_add_f32_e32 v184, v234, v235
	v_add_f32_e32 v183, 0, v183
	v_mul_f32_e32 v252, v13, v145
	v_mul_f32_e32 v253, v15, v147
	v_add_f32_e32 v183, v183, v184
	v_add_f32_e32 v184, v199, v200
	v_fmac_f32_e32 v252, v12, v144
	v_fmac_f32_e32 v253, v14, v146
	v_add_f32_e32 v183, v183, v184
	v_add_f32_e32 v184, v215, v216
	v_cndmask_b32_e64 v186, v159, v181, s[2:3]
	v_cndmask_b32_e64 v159, v181, v159, s[2:3]
	v_cndmask_b32_e64 v181, v176, v182, s[2:3]
	v_add_f32_e32 v183, v183, v184
	v_add_f32_e32 v184, v252, v253
	ds_bpermute_b32 v181, v164, v181
	v_add_f32_e32 v185, v236, v237
	v_add_f32_e32 v184, 0, v184
	v_add_f32_e32 v174, v174, v175
	v_add_f32_e32 v184, v184, v185
	v_add_f32_e32 v185, v201, v202
	ds_bpermute_b32 v175, v169, v174
	v_add_f32_e32 v184, v184, v185
	v_add_f32_e32 v185, v217, v218
	v_add_f32_e32 v184, v184, v185
	v_cndmask_b32_e64 v176, v182, v176, s[2:3]
	v_cndmask_b32_e64 v182, v177, v183, s[2:3]
	s_waitcnt lgkmcnt(1)
	v_add_f32_e32 v176, v176, v181
	v_cndmask_b32_e64 v181, v180, v184, s[2:3]
	ds_bpermute_b32 v186, v164, v186
	ds_bpermute_b32 v182, v164, v182
	ds_bpermute_b32 v181, v164, v181
	s_waitcnt lgkmcnt(3)
	v_add_f32_e32 v174, v174, v175
	ds_bpermute_b32 v175, v168, v174
	v_cndmask_b32_e64 v177, v183, v177, s[2:3]
	v_cndmask_b32_e64 v180, v184, v180, s[2:3]
	s_waitcnt lgkmcnt(3)
	v_add_f32_e32 v159, v159, v186
	s_waitcnt lgkmcnt(2)
	v_add_f32_e32 v177, v177, v182
	s_waitcnt lgkmcnt(1)
	v_add_f32_e32 v180, v180, v181
	v_cndmask_b32_e64 v181, v159, v177, s[4:5]
	v_cndmask_b32_e64 v159, v177, v159, s[4:5]
	v_cndmask_b32_e64 v177, v176, v180, s[4:5]
	ds_bpermute_b32 v181, v165, v181
	ds_bpermute_b32 v177, v165, v177
	s_waitcnt lgkmcnt(2)
	v_add_f32_e32 v174, v174, v175
	ds_bpermute_b32 v175, v167, v174
	v_cndmask_b32_e64 v176, v180, v176, s[4:5]
	s_waitcnt lgkmcnt(2)
	v_add_f32_e32 v159, v159, v181
	s_waitcnt lgkmcnt(1)
	v_add_f32_e32 v176, v176, v177
	v_cndmask_b32_e64 v177, v159, v176, s[6:7]
	s_waitcnt lgkmcnt(0)
	v_add_f32_e32 v180, v174, v175
	ds_bpermute_b32 v177, v166, v177
	ds_bpermute_b32 v181, v166, v180
	v_cndmask_b32_e64 v159, v176, v159, s[6:7]
	v_lshl_add_u64 v[174:175], s[84:85], 0, v[154:155]
	v_add_co_u32_e32 v174, vcc, s27, v174
	s_waitcnt lgkmcnt(1)
	v_add_f32_e32 v159, v159, v177
	s_waitcnt lgkmcnt(0)
	v_add_f32_e32 v177, v180, v181
	ds_bpermute_b32 v180, v165, v177
	ds_bpermute_b32 v176, v167, v159
	v_addc_co_u32_e32 v175, vcc, 0, v175, vcc
	v_cvt_pk_bf16_f32 v144, v144, v145
	s_waitcnt lgkmcnt(1)
	v_add_f32_e32 v177, v177, v180
	ds_bpermute_b32 v180, v164, v177
	s_waitcnt lgkmcnt(1)
	v_add_f32_e32 v159, v159, v176
	ds_bpermute_b32 v176, v168, v159
	v_cvt_pk_bf16_f32 v145, v146, v147
	global_store_dwordx2 v[174:175], v[144:145], off
	global_store_dwordx2 v[174:175], v[178:179], off offset:512
	s_waitcnt lgkmcnt(1)
	v_add_f32_e32 v144, v177, v180
	v_fmamk_f32 v144, v144, 0x3a800000, v170
	v_mul_f32_e32 v146, 0x4b800000, v144
	v_cmp_gt_f32_e32 vcc, s33, v144
	s_waitcnt lgkmcnt(0)
	v_add_f32_e32 v145, v159, v176
	global_store_dwordx2 v[174:175], v[160:161], off offset:1024
	global_store_dwordx2 v[174:175], v[162:163], off offset:1536
	v_cndmask_b32_e32 v144, v144, v146, vcc
	v_rsq_f32_e32 v144, v144
	ds_bpermute_b32 v146, v169, v145
	v_mul_f32_e32 v147, 0x45800000, v144
	v_cndmask_b32_e32 v144, v144, v147, vcc
	s_and_saveexec_b64 s[48:49], s[8:9]
	s_cbranch_execz .LBB0_70
	v_mov_b32_e32 v147, v254
	s_waitcnt lgkmcnt(0)
	v_add_f32_e32 v145, v145, v146
	s_and_b64 s[44:45], s[44:45], exec
	s_cselect_b32 s44, s52, 0x24e00000
	s_add_u32 s44, s22, s44
	s_addc_u32 s45, s23, 0
	s_lshl_b64 s[20:21], s[20:21], 5
	s_add_u32 s20, s44, s20
	s_addc_u32 s21, s45, s21
	v_fmac_f32_e32 v147, v145, v144
	v_mul_f32_e64 v145, |v147|, s34
	v_fma_f32 v146, |v147|, s34, -v145
	v_rndne_f32_e32 v159, v145
	v_fma_f32 v146, |v147|, s35, v146
	v_sub_f32_e32 v145, v145, v159
	v_add_f32_e32 v145, v145, v146
	v_cvt_i32_f32_e32 v159, v159
	v_exp_f32_e32 v145, v145
	v_cmp_ngt_f32_e64 vcc, |v147|, s36
	v_min_f32_e32 v182, 0, v147
	v_ldexp_f32 v145, v145, v159
	v_cndmask_b32_e32 v145, 0, v145, vcc
	v_cmp_nlt_f32_e64 vcc, |v147|, s37
	s_nop 1
	v_cndmask_b32_e32 v145, v173, v145, vcc
	v_add_f32_e32 v159, 1.0, v145
	v_add_f32_e32 v160, -1.0, v159
	v_frexp_mant_f32_e32 v161, v159
	v_cvt_f64_f32_e32 v[146:147], v159
	v_sub_f32_e32 v162, v160, v159
	v_frexp_exp_i32_f64_e32 v146, v[146:147]
	v_cmp_gt_f32_e32 vcc, s39, v161
	v_sub_f32_e32 v160, v145, v160
	v_add_f32_e32 v147, 1.0, v162
	v_subbrev_co_u32_e32 v146, vcc, 0, v146, vcc
	v_add_f32_e32 v147, v160, v147
	v_sub_u32_e32 v160, 0, v146
	v_ldexp_f32 v159, v159, v160
	v_ldexp_f32 v147, v147, v160
	v_add_f32_e32 v160, -1.0, v159
	v_add_f32_e32 v162, 1.0, v159
	v_add_f32_e32 v161, 1.0, v160
	v_add_f32_e32 v163, -1.0, v162
	v_sub_f32_e32 v161, v159, v161
	v_sub_f32_e32 v159, v159, v163
	v_add_f32_e32 v163, v147, v161
	v_add_f32_e32 v147, v147, v159
	v_add_f32_e32 v159, v162, v147
	v_rcp_f32_e32 v176, v159
	v_add_f32_e32 v161, v160, v163
	v_sub_f32_e32 v162, v162, v159
	v_add_f32_e32 v147, v147, v162
	v_mul_f32_e32 v178, v161, v176
	v_mul_f32_e32 v162, v159, v178
	v_fma_f32 v174, v178, v159, -v162
	v_sub_f32_e32 v160, v160, v161
	v_fmac_f32_e32 v174, v178, v147
	v_add_f32_e32 v177, v163, v160
	v_add_f32_e32 v160, v162, v174
	v_sub_f32_e32 v163, v161, v160
	v_mov_b32_e32 v175, v160
	v_pk_add_f32 v[160:161], v[160:161], v[162:163] neg_lo:[0,1] neg_hi:[0,1]
	v_cvt_f32_i32_e32 v146, v146
	v_pk_add_f32 v[160:161], v[160:161], v[174:175] neg_lo:[0,1] neg_hi:[0,1]
	v_cmp_neq_f32_e32 vcc, s38, v145
	v_add_f32_e32 v161, v177, v161
	v_add_f32_e32 v160, v160, v161
	v_add_f32_e32 v161, v163, v160
	v_mul_f32_e32 v175, v176, v161
	v_mul_f32_e32 v162, v159, v175
	v_fma_f32 v174, v175, v159, -v162
	v_sub_f32_e32 v163, v163, v161
	v_fmac_f32_e32 v174, v175, v147
	v_add_f32_e32 v177, v160, v163
	v_add_f32_e32 v179, v178, v175
	v_add_f32_e32 v160, v162, v174
	v_sub_f32_e32 v159, v179, v178
	v_sub_f32_e32 v163, v161, v160
	v_sub_f32_e32 v147, v175, v159
	v_mov_b32_e32 v175, v160
	v_pk_add_f32 v[160:161], v[160:161], v[162:163] neg_lo:[0,1] neg_hi:[0,1]
	s_nop 0
	v_pk_add_f32 v[160:161], v[160:161], v[174:175] neg_lo:[0,1] neg_hi:[0,1]
	s_nop 0
	v_add_f32_e32 v159, v177, v161
	v_add_f32_e32 v159, v160, v159
	v_add_f32_e32 v159, v163, v159
	v_mul_f32_e32 v159, v176, v159
	v_add_f32_e32 v147, v147, v159
	v_add_f32_e32 v159, v179, v147
	v_mul_f32_e32 v160, v159, v159
	v_sub_f32_e32 v162, v159, v179
	v_fmamk_f32 v163, v160, 0x3e9b6dac, v171
	v_ldexp_f32 v161, v159, 1
	v_sub_f32_e32 v162, v147, v162
	v_mul_f32_e32 v147, v159, v160
	v_fmaak_f32 v159, v160, v163, 0x3f2aaada
	v_ldexp_f32 v175, v162, 1
	v_pk_mul_f32 v[162:163], v[146:147], v[158:159]
	s_nop 0
	v_fma_f32 v160, v146, s50, -v162
	v_fmac_f32_e32 v160, 0xb102e308, v146
	v_pk_add_f32 v[146:147], v[162:163], v[160:161]
	v_mov_b32_e32 v174, v162
	v_sub_f32_e32 v159, v147, v161
	v_sub_f32_e32 v159, v163, v159
	v_add_f32_e32 v175, v175, v159
	v_pk_add_f32 v[176:177], v[146:147], v[162:163] neg_lo:[0,1] neg_hi:[0,1]
	v_pk_add_f32 v[162:163], v[146:147], v[174:175]
	v_mov_b32_e32 v161, v146
	v_mov_b32_e32 v177, v163
	v_pk_add_f32 v[180:181], v[160:161], v[176:177] neg_lo:[0,1] neg_hi:[0,1]
	v_pk_add_f32 v[160:161], v[160:161], v[176:177]
	v_mov_b32_e32 v179, v146
	v_pk_add_f32 v[176:177], v[160:161], v[146:147] op_sel:[1,0] op_sel_hi:[0,1] neg_lo:[0,1] neg_hi:[0,1]
	v_mov_b32_e32 v178, v175
	v_mov_b32_e32 v174, v163
	v_mov_b32_e32 v175, v161
	v_pk_mov_b32 v[146:147], v[146:147], v[176:177] op_sel:[1,0]
	v_pk_add_f32 v[162:163], v[162:163], v[176:177] op_sel_hi:[1,0] neg_lo:[0,1] neg_hi:[0,1]
	v_pk_add_f32 v[146:147], v[174:175], v[146:147] neg_lo:[0,1] neg_hi:[0,1]
	v_mov_b32_e32 v162, v180
	v_pk_add_f32 v[146:147], v[178:179], v[146:147] neg_lo:[0,1] neg_hi:[0,1]
	v_mov_b32_e32 v181, v161
	v_pk_add_f32 v[162:163], v[162:163], v[146:147]
	s_nop 0
	v_pk_add_f32 v[174:175], v[162:163], v[162:163] op_sel:[0,1] op_sel_hi:[1,0]
	s_nop 0
	v_pk_add_f32 v[160:161], v[160:161], v[174:175] op_sel:[1,0] op_sel_hi:[0,1]
	v_mov_b32_e32 v163, v160
	v_mov_b32_e32 v147, v174
	v_pk_add_f32 v[174:175], v[162:163], v[180:181] neg_lo:[0,1] neg_hi:[0,1]
	s_nop 0
	v_sub_f32_e32 v159, v162, v174
	v_pk_add_f32 v[146:147], v[146:147], v[174:175] neg_lo:[0,1] neg_hi:[0,1]
	v_sub_f32_e32 v159, v180, v159
	v_add_f32_e32 v146, v146, v159
	v_add_f32_e32 v146, v146, v147
	v_add_f32_e32 v146, v160, v146
	v_cndmask_b32_e32 v146, v173, v146, vcc
	v_cmp_lt_f32_e64 vcc, |v145|, s51
	s_nop 1
	v_cndmask_b32_e32 v145, v146, v145, vcc
	v_sub_f32_e32 v145, v182, v145
	v_lshl_add_u64 v[146:147], v[148:149], 2, s[20:21]
	global_store_dword v[146:147], v145, off
	s_or_b64 exec, exec, s[48:49]
	s_and_saveexec_b64 s[20:21], s[10:11]
	s_cbranch_execnz .LBB0_71

.LBB0_72:
	s_waitcnt vmcnt(6)
	v_pk_mul_f32 v[144:145], v[138:139], v[138:139]
	s_waitcnt lgkmcnt(0)
	v_pk_mul_f32 v[146:147], v[136:137], v[136:137]
	v_pk_mul_f32 v[162:163], v[142:143], v[142:143]
	v_pk_mul_f32 v[174:175], v[140:141], v[140:141]
	v_pk_mov_b32 v[160:161], v[146:147], v[144:145] op_sel:[1,0]
	v_mov_b32_e32 v147, v145
	v_lshl_add_u64 v[144:145], s[84:85], 0, v[152:153]
	v_pk_mov_b32 v[176:177], v[174:175], v[162:163] op_sel:[1,0]
	v_mov_b32_e32 v175, v163
	v_add_co_u32_e32 v144, vcc, s27, v144
	v_pk_add_f32 v[162:163], v[176:177], v[174:175]
	v_pk_add_f32 v[160:161], v[160:161], v[146:147]
	s_waitcnt vmcnt(4)
	v_mul_f32_e32 v159, v128, v128
	v_cvt_pk_bf16_f32 v146, v140, v141
	v_cvt_pk_bf16_f32 v147, v142, v143
	v_addc_co_u32_e32 v145, vcc, 0, v145, vcc
	v_pk_add_f32 v[162:163], v[162:163], v[162:163] op_sel:[0,1] op_sel_hi:[1,0]
	v_mul_f32_e32 v178, v129, v129
	global_store_dwordx2 v[144:145], v[146:147], off
	v_mov_b32_e32 v163, v159
	v_pk_add_f32 v[160:161], v[160:161], v[160:161] op_sel:[0,1] op_sel_hi:[1,0]
	v_mul_f32_e32 v147, v125, v141
	v_mul_f32_e32 v159, v127, v143
	v_mov_b32_e32 v161, v178
	v_fmac_f32_e32 v147, v124, v140
	v_fmac_f32_e32 v159, v126, v142
	v_pk_add_f32 v[160:161], v[162:163], v[160:161]
	v_add_f32_e32 v147, v147, v159
	v_mul_f32_e32 v159, v121, v137
	v_mul_f32_e32 v162, v123, v139
	v_fmac_f32_e32 v159, v120, v136
	v_fmac_f32_e32 v162, v122, v138
	v_add_f32_e32 v147, 0, v147
	v_add_f32_e32 v159, v159, v162
	v_add_f32_e32 v147, v147, v159
	v_mul_f32_e32 v159, v117, v133
	v_mul_f32_e32 v162, v119, v135
	v_fmac_f32_e32 v159, v116, v132
	v_fmac_f32_e32 v162, v118, v134
	v_add_f32_e32 v159, v159, v162
	v_add_f32_e32 v147, v147, v159
	v_mul_f32_e32 v159, v113, v129
	v_mul_f32_e32 v162, v115, v131
	v_fmac_f32_e32 v159, v112, v128
	v_fmac_f32_e32 v162, v114, v130
	v_add_f32_e32 v159, v159, v162
	v_add_f32_e32 v147, v147, v159
	v_mul_f32_e32 v159, v109, v141
	v_mul_f32_e32 v162, v111, v143
	v_fmac_f32_e32 v159, v108, v140
	v_fmac_f32_e32 v162, v110, v142
	v_add_f32_e32 v159, v159, v162
	v_mul_f32_e32 v162, v105, v137
	v_mul_f32_e32 v163, v107, v139
	v_fmac_f32_e32 v162, v104, v136
	v_fmac_f32_e32 v163, v106, v138
	v_add_f32_e32 v159, 0, v159
	v_add_f32_e32 v162, v162, v163
	v_add_f32_e32 v159, v159, v162
	v_mul_f32_e32 v162, v101, v133
	v_mul_f32_e32 v163, v103, v135
	v_fmac_f32_e32 v162, v100, v132
	v_fmac_f32_e32 v163, v102, v134
	v_add_f32_e32 v162, v162, v163
	v_add_f32_e32 v159, v159, v162
	v_mul_f32_e32 v162, v97, v129
	v_mul_f32_e32 v163, v99, v131
	v_mul_f32_e32 v174, v133, v133
	v_mul_f32_e32 v176, v135, v135
	v_fmac_f32_e32 v162, v96, v128
	v_fmac_f32_e32 v163, v98, v130
	v_mul_f32_e32 v179, v130, v130
	v_mul_f32_e32 v180, v131, v131
	v_pk_fma_f32 v[174:175], v[132:133], v[132:133], v[174:175] op_sel_hi:[1,1,0]
	v_pk_fma_f32 v[176:177], v[134:135], v[134:135], v[176:177] op_sel_hi:[1,1,0]
	v_add_f32_e32 v162, v162, v163
	v_mov_b32_e32 v175, v179
	v_mov_b32_e32 v177, v180
	v_add_f32_e32 v159, v159, v162
	v_mul_f32_e32 v162, v93, v141
	v_mul_f32_e32 v163, v95, v143
	v_pk_add_f32 v[174:175], v[174:175], v[176:177]
	v_fmac_f32_e32 v162, v92, v140
	v_fmac_f32_e32 v163, v94, v142
	v_pk_add_f32 v[160:161], v[160:161], v[174:175]
	v_add_f32_e32 v162, v162, v163
	v_mul_f32_e32 v163, v89, v137
	v_mul_f32_e32 v174, v91, v139
	v_fmac_f32_e32 v163, v88, v136
	v_fmac_f32_e32 v174, v90, v138
	v_add_f32_e32 v162, 0, v162
	v_add_f32_e32 v163, v163, v174
	v_add_f32_e32 v162, v162, v163
	v_mul_f32_e32 v163, v85, v133
	v_mul_f32_e32 v174, v87, v135
	v_fmac_f32_e32 v163, v84, v132
	v_fmac_f32_e32 v174, v86, v134
	v_add_f32_e32 v163, v163, v174
	v_add_f32_e32 v162, v162, v163
	v_mul_f32_e32 v163, v81, v129
	v_mul_f32_e32 v174, v83, v131
	v_fmac_f32_e32 v163, v80, v128
	v_fmac_f32_e32 v174, v82, v130
	v_add_f32_e32 v163, v163, v174
	v_add_f32_e32 v162, v162, v163
	v_mul_f32_e32 v163, v77, v141
	v_mul_f32_e32 v174, v79, v143
	v_fmac_f32_e32 v163, v76, v140
	v_fmac_f32_e32 v174, v78, v142
	v_add_f32_e32 v163, v163, v174
	v_mul_f32_e32 v174, v73, v137
	v_mul_f32_e32 v175, v75, v139
	v_fmac_f32_e32 v174, v72, v136
	v_fmac_f32_e32 v175, v74, v138
	v_add_f32_e32 v163, 0, v163
	v_add_f32_e32 v174, v174, v175
	v_add_f32_e32 v163, v163, v174
	v_mul_f32_e32 v174, v69, v133
	v_mul_f32_e32 v175, v71, v135
	v_fmac_f32_e32 v174, v68, v132
	v_fmac_f32_e32 v175, v70, v134
	v_add_f32_e32 v174, v174, v175
	v_add_f32_e32 v163, v163, v174
	v_mul_f32_e32 v174, v65, v129
	v_mul_f32_e32 v175, v67, v131
	v_fmac_f32_e32 v174, v64, v128
	v_fmac_f32_e32 v175, v66, v130
	v_add_f32_e32 v174, v174, v175
	v_add_f32_e32 v163, v163, v174
	v_mul_f32_e32 v174, v61, v141
	v_mul_f32_e32 v175, v63, v143
	v_fmac_f32_e32 v174, v60, v140
	v_fmac_f32_e32 v175, v62, v142
	v_add_f32_e32 v174, v174, v175
	v_mul_f32_e32 v175, v57, v137
	v_mul_f32_e32 v176, v59, v139
	v_fmac_f32_e32 v175, v56, v136
	v_fmac_f32_e32 v176, v58, v138
	v_add_f32_e32 v174, 0, v174
	v_add_f32_e32 v175, v175, v176
	v_add_f32_e32 v174, v174, v175
	v_mul_f32_e32 v175, v53, v133
	v_mul_f32_e32 v176, v55, v135
	v_fmac_f32_e32 v175, v52, v132
	v_fmac_f32_e32 v176, v54, v134
	v_add_f32_e32 v175, v175, v176
	v_add_f32_e32 v174, v174, v175
	v_mul_f32_e32 v175, v49, v129
	v_mul_f32_e32 v176, v51, v131
	v_fmac_f32_e32 v175, v48, v128
	v_fmac_f32_e32 v176, v50, v130
	v_add_f32_e32 v175, v175, v176
	v_add_f32_e32 v174, v174, v175
	v_mul_f32_e32 v175, v45, v141
	v_mul_f32_e32 v176, v47, v143
	v_fmac_f32_e32 v175, v44, v140
	v_fmac_f32_e32 v176, v46, v142
	v_add_f32_e32 v175, v175, v176
	v_mul_f32_e32 v176, v41, v137
	v_mul_f32_e32 v177, v43, v139
	v_fmac_f32_e32 v176, v40, v136
	v_fmac_f32_e32 v177, v42, v138
	v_add_f32_e32 v175, 0, v175
	v_add_f32_e32 v176, v176, v177
	v_add_f32_e32 v175, v175, v176
	v_mul_f32_e32 v176, v37, v133
	v_mul_f32_e32 v177, v39, v135
	v_fmac_f32_e32 v176, v36, v132
	v_fmac_f32_e32 v177, v38, v134
	v_add_f32_e32 v176, v176, v177
	v_add_f32_e32 v175, v175, v176
	v_mul_f32_e32 v176, v33, v129
	v_mul_f32_e32 v177, v35, v131
	v_fmac_f32_e32 v176, v32, v128
	v_fmac_f32_e32 v177, v34, v130
	v_add_f32_e32 v176, v176, v177
	v_add_f32_e32 v175, v175, v176
	v_mul_f32_e32 v176, v29, v141
	v_mul_f32_e32 v177, v31, v143
	v_fmac_f32_e32 v176, v28, v140
	v_fmac_f32_e32 v177, v30, v142
	v_mul_f32_e32 v141, v13, v141
	v_cvt_pk_bf16_f32 v146, v136, v137
	v_add_f32_e32 v176, v176, v177
	v_mul_f32_e32 v177, v25, v137
	v_fmac_f32_e32 v141, v12, v140
	v_mul_f32_e32 v140, v15, v143
	v_mul_f32_e32 v137, v9, v137
	v_fmac_f32_e32 v177, v24, v136
	v_mul_f32_e32 v178, v27, v139
	v_fmac_f32_e32 v140, v14, v142
	v_fmac_f32_e32 v137, v8, v136
	v_mul_f32_e32 v136, v11, v139
	v_fmac_f32_e32 v178, v26, v138
	v_add_f32_e32 v140, v141, v140
	v_fmac_f32_e32 v136, v10, v138
	v_add_f32_e32 v176, 0, v176
	v_add_f32_e32 v177, v177, v178
	v_add_f32_e32 v140, 0, v140
	v_add_f32_e32 v136, v137, v136
	v_add_f32_e32 v176, v176, v177
	v_mul_f32_e32 v177, v21, v133
	v_mul_f32_e32 v178, v23, v135
	v_add_f32_e32 v136, v140, v136
	v_mul_f32_e32 v137, v5, v133
	v_mul_f32_e32 v140, v7, v135
	v_fmac_f32_e32 v177, v20, v132
	v_fmac_f32_e32 v178, v22, v134
	v_fmac_f32_e32 v137, v4, v132
	v_fmac_f32_e32 v140, v6, v134
	v_add_f32_e32 v177, v177, v178
	v_add_f32_e32 v137, v137, v140
	v_add_f32_e32 v176, v176, v177
	v_mul_f32_e32 v177, v17, v129
	v_mul_f32_e32 v178, v19, v131
	v_add_f32_e32 v136, v136, v137
	v_mul_f32_e32 v137, v1, v129
	v_mul_f32_e32 v140, v3, v131
	v_fmac_f32_e32 v177, v16, v128
	v_fmac_f32_e32 v178, v18, v130
	v_fmac_f32_e32 v137, v0, v128
	v_fmac_f32_e32 v140, v2, v130
	v_add_f32_e32 v177, v177, v178
	v_add_f32_e32 v137, v137, v140
	v_cndmask_b32_e64 v140, v147, v174, s[2:3]
	v_add_f32_e32 v176, v176, v177
	ds_bpermute_b32 v140, v164, v140
	v_cndmask_b32_e64 v141, v159, v175, s[2:3]
	ds_bpermute_b32 v141, v164, v141
	v_cndmask_b32_e64 v142, v162, v176, s[2:3]
	ds_bpermute_b32 v142, v164, v142
	v_add_f32_e32 v136, v136, v137
	v_cndmask_b32_e64 v137, v174, v147, s[2:3]
	s_waitcnt lgkmcnt(2)
	v_add_f32_e32 v137, v137, v140
	v_cndmask_b32_e64 v140, v175, v159, s[2:3]
	s_waitcnt lgkmcnt(1)
	v_add_f32_e32 v140, v140, v141
	v_cndmask_b32_e64 v141, v176, v162, s[2:3]
	s_waitcnt lgkmcnt(0)
	v_add_f32_e32 v141, v141, v142
	v_add_f32_e32 v142, v160, v161
	v_cndmask_b32_e64 v143, v163, v136, s[2:3]
	ds_bpermute_b32 v147, v169, v142
	ds_bpermute_b32 v143, v164, v143
	v_cndmask_b32_e64 v136, v136, v163, s[2:3]
	v_cvt_pk_bf16_f32 v132, v132, v133
	v_cvt_pk_bf16_f32 v133, v134, v135
	s_waitcnt lgkmcnt(1)
	v_add_f32_e32 v142, v142, v147
	s_waitcnt lgkmcnt(0)
	v_add_f32_e32 v136, v136, v143
	v_cndmask_b32_e64 v143, v137, v141, s[4:5]
	ds_bpermute_b32 v147, v168, v142
	ds_bpermute_b32 v143, v165, v143
	v_cndmask_b32_e64 v137, v141, v137, s[4:5]
	v_cndmask_b32_e64 v141, v140, v136, s[4:5]
	ds_bpermute_b32 v141, v165, v141
	s_waitcnt lgkmcnt(2)
	v_add_f32_e32 v142, v142, v147
	s_waitcnt lgkmcnt(1)
	v_add_f32_e32 v137, v137, v143
	ds_bpermute_b32 v143, v167, v142
	v_cndmask_b32_e64 v136, v136, v140, s[4:5]
	s_waitcnt lgkmcnt(1)
	v_add_f32_e32 v136, v136, v141
	v_cndmask_b32_e64 v140, v137, v136, s[6:7]
	ds_bpermute_b32 v140, v166, v140
	s_waitcnt lgkmcnt(1)
	v_add_f32_e32 v141, v142, v143
	ds_bpermute_b32 v142, v166, v141
	v_cvt_pk_bf16_f32 v147, v138, v139
	v_cndmask_b32_e64 v136, v136, v137, s[6:7]
	s_waitcnt lgkmcnt(1)
	v_add_f32_e32 v136, v136, v140
	ds_bpermute_b32 v137, v167, v136
	s_waitcnt lgkmcnt(1)
	v_add_f32_e32 v138, v141, v142
	ds_bpermute_b32 v139, v165, v138
	v_cvt_pk_bf16_f32 v134, v128, v129
	global_store_dwordx2 v[144:145], v[132:133], off offset:1024
	s_waitcnt lgkmcnt(1)
	v_add_f32_e32 v136, v136, v137
	ds_bpermute_b32 v137, v168, v136
	s_waitcnt lgkmcnt(1)
	v_add_f32_e32 v138, v138, v139
	ds_bpermute_b32 v139, v164, v138
	v_cvt_pk_bf16_f32 v135, v130, v131
	global_store_dwordx2 v[144:145], v[146:147], off offset:512
	s_waitcnt lgkmcnt(1)
	v_add_f32_e32 v129, v136, v137
	global_store_dwordx2 v[144:145], v[134:135], off offset:1536
	s_waitcnt lgkmcnt(0)
	v_add_f32_e32 v128, v138, v139
	v_fmamk_f32 v128, v128, 0x3a800000, v170
	v_mul_f32_e32 v132, 0x4b800000, v128
	v_cmp_gt_f32_e32 vcc, s33, v128
	s_nop 1
	v_cndmask_b32_e32 v128, v128, v132, vcc
	v_rsq_f32_e32 v128, v128
	ds_bpermute_b32 v132, v169, v129
	v_mul_f32_e32 v130, 0x45800000, v128
	v_cndmask_b32_e32 v128, v128, v130, vcc
	s_and_saveexec_b64 s[20:21], s[8:9]
	s_cbranch_execz .LBB0_74
	v_mov_b32_e32 v130, v254
	s_waitcnt lgkmcnt(0)
	v_add_f32_e32 v129, v129, v132
	s_add_u32 s44, s28, s42
	s_addc_u32 s45, s29, s43
	s_add_i32 s46, s54, 0xffff0000
	s_cmp_lt_i32 s54, 0x10000
	s_cselect_b32 s44, s44, s46
	s_cselect_b32 s46, s52, 0x24e00000
	s_cselect_b32 s45, s45, 0
	s_add_u32 s46, s22, s46
	s_addc_u32 s47, s23, 0
	s_lshl_b64 s[44:45], s[44:45], 5
	s_add_u32 s44, s46, s44
	s_addc_u32 s45, s47, s45
	v_fmac_f32_e32 v130, v129, v128
	v_mul_f32_e64 v129, |v130|, s34
	v_fma_f32 v131, |v130|, s34, -v129
	v_rndne_f32_e32 v132, v129
	v_fma_f32 v131, |v130|, s35, v131
	v_sub_f32_e32 v129, v129, v132
	v_add_f32_e32 v129, v129, v131
	v_cvt_i32_f32_e32 v132, v132
	v_exp_f32_e32 v129, v129
	v_cmp_ngt_f32_e64 vcc, |v130|, s36
	v_min_f32_e32 v144, 0, v130
	v_ldexp_f32 v129, v129, v132
	v_cndmask_b32_e32 v129, 0, v129, vcc
	v_cmp_nlt_f32_e64 vcc, |v130|, s37
	s_nop 1
	v_cndmask_b32_e32 v129, v173, v129, vcc
	v_add_f32_e32 v132, 1.0, v129
	v_add_f32_e32 v133, -1.0, v132
	v_frexp_mant_f32_e32 v134, v132
	v_cvt_f64_f32_e32 v[130:131], v132
	v_sub_f32_e32 v135, v133, v132
	v_frexp_exp_i32_f64_e32 v130, v[130:131]
	v_cmp_gt_f32_e32 vcc, s39, v134
	v_sub_f32_e32 v133, v129, v133
	v_add_f32_e32 v131, 1.0, v135
	v_subbrev_co_u32_e32 v130, vcc, 0, v130, vcc
	v_add_f32_e32 v131, v133, v131
	v_sub_u32_e32 v133, 0, v130
	v_ldexp_f32 v132, v132, v133
	v_add_f32_e32 v134, -1.0, v132
	v_add_f32_e32 v135, 1.0, v132
	v_ldexp_f32 v131, v131, v133
	v_add_f32_e32 v133, 1.0, v134
	v_add_f32_e32 v136, -1.0, v135
	v_sub_f32_e32 v133, v132, v133
	v_sub_f32_e32 v132, v132, v136
	v_add_f32_e32 v136, v131, v133
	v_add_f32_e32 v131, v131, v132
	v_add_f32_e32 v138, v135, v131
	v_rcp_f32_e32 v139, v138
	v_add_f32_e32 v133, v134, v136
	v_sub_f32_e32 v134, v134, v133
	v_sub_f32_e32 v132, v135, v138
	v_mul_f32_e32 v141, v133, v139
	v_add_f32_e32 v140, v136, v134
	v_mul_f32_e32 v134, v138, v141
	v_add_f32_e32 v131, v131, v132
	v_fma_f32 v136, v141, v138, -v134
	v_fmac_f32_e32 v136, v141, v131
	v_add_f32_e32 v132, v134, v136
	v_sub_f32_e32 v135, v133, v132
	v_mov_b32_e32 v137, v132
	v_pk_add_f32 v[132:133], v[132:133], v[134:135] neg_lo:[0,1] neg_hi:[0,1]
	v_cvt_f32_i32_e32 v130, v130
	v_pk_add_f32 v[132:133], v[132:133], v[136:137] neg_lo:[0,1] neg_hi:[0,1]
	v_cmp_neq_f32_e32 vcc, s38, v129
	v_add_f32_e32 v133, v140, v133
	v_add_f32_e32 v132, v132, v133
	v_add_f32_e32 v133, v135, v132
	v_mul_f32_e32 v137, v139, v133
	v_mul_f32_e32 v134, v138, v137
	v_sub_f32_e32 v135, v135, v133
	v_add_f32_e32 v142, v141, v137
	v_fma_f32 v136, v137, v138, -v134
	v_add_f32_e32 v140, v132, v135
	v_sub_f32_e32 v132, v142, v141
	v_fmac_f32_e32 v136, v137, v131
	v_sub_f32_e32 v131, v137, v132
	v_add_f32_e32 v132, v134, v136
	v_sub_f32_e32 v135, v133, v132
	v_mov_b32_e32 v137, v132
	v_pk_add_f32 v[132:133], v[132:133], v[134:135] neg_lo:[0,1] neg_hi:[0,1]
	s_nop 0
	v_pk_add_f32 v[132:133], v[132:133], v[136:137] neg_lo:[0,1] neg_hi:[0,1]
	s_nop 0
	v_add_f32_e32 v133, v140, v133
	v_add_f32_e32 v132, v132, v133
	v_add_f32_e32 v132, v135, v132
	v_mul_f32_e32 v132, v139, v132
	v_add_f32_e32 v131, v131, v132
	v_add_f32_e32 v132, v142, v131
	v_mul_f32_e32 v134, v132, v132
	v_sub_f32_e32 v135, v132, v142
	v_fmamk_f32 v136, v134, 0x3e9b6dac, v171
	v_sub_f32_e32 v135, v131, v135
	v_mul_f32_e32 v131, v132, v134
	v_fmaak_f32 v159, v134, v136, 0x3f2aaada
	v_ldexp_f32 v137, v135, 1
	v_pk_mul_f32 v[134:135], v[130:131], v[158:159]
	v_ldexp_f32 v133, v132, 1
	v_fma_f32 v132, v130, s50, -v134
	v_fmac_f32_e32 v132, 0xb102e308, v130
	v_pk_add_f32 v[130:131], v[134:135], v[132:133]
	v_mov_b32_e32 v136, v134
	v_sub_f32_e32 v140, v131, v133
	v_pk_add_f32 v[138:139], v[130:131], v[134:135] neg_lo:[0,1] neg_hi:[0,1]
	v_sub_f32_e32 v134, v135, v140
	v_add_f32_e32 v137, v137, v134
	v_pk_add_f32 v[134:135], v[130:131], v[136:137]
	v_mov_b32_e32 v133, v130
	v_mov_b32_e32 v139, v135
	v_pk_add_f32 v[142:143], v[132:133], v[138:139] neg_lo:[0,1] neg_hi:[0,1]
	v_pk_add_f32 v[132:133], v[132:133], v[138:139]
	v_mov_b32_e32 v141, v130
	v_pk_add_f32 v[138:139], v[132:133], v[130:131] op_sel:[1,0] op_sel_hi:[0,1] neg_lo:[0,1] neg_hi:[0,1]
	v_mov_b32_e32 v140, v137
	v_mov_b32_e32 v136, v135
	v_mov_b32_e32 v137, v133
	v_pk_mov_b32 v[130:131], v[130:131], v[138:139] op_sel:[1,0]
	v_pk_add_f32 v[134:135], v[134:135], v[138:139] op_sel_hi:[1,0] neg_lo:[0,1] neg_hi:[0,1]
	v_pk_add_f32 v[130:131], v[136:137], v[130:131] neg_lo:[0,1] neg_hi:[0,1]
	v_mov_b32_e32 v134, v142
	v_pk_add_f32 v[130:131], v[140:141], v[130:131] neg_lo:[0,1] neg_hi:[0,1]
	v_mov_b32_e32 v143, v133
	v_pk_add_f32 v[134:135], v[134:135], v[130:131]
	s_nop 0
	v_pk_add_f32 v[136:137], v[134:135], v[134:135] op_sel:[0,1] op_sel_hi:[1,0]
	s_nop 0
	v_pk_add_f32 v[132:133], v[132:133], v[136:137] op_sel:[1,0] op_sel_hi:[0,1]
	v_mov_b32_e32 v135, v132
	v_mov_b32_e32 v131, v136
	v_pk_add_f32 v[136:137], v[134:135], v[142:143] neg_lo:[0,1] neg_hi:[0,1]
	s_nop 0
	v_sub_f32_e32 v133, v134, v136
	v_pk_add_f32 v[130:131], v[130:131], v[136:137] neg_lo:[0,1] neg_hi:[0,1]
	v_sub_f32_e32 v133, v142, v133
	v_add_f32_e32 v130, v130, v133
	v_add_f32_e32 v130, v130, v131
	v_add_f32_e32 v130, v132, v130
	v_cndmask_b32_e32 v130, v173, v130, vcc
	v_cmp_lt_f32_e64 vcc, |v129|, s51
	s_nop 1
	v_cndmask_b32_e32 v129, v130, v129, vcc
	v_sub_f32_e32 v129, v144, v129
	v_lshl_add_u64 v[130:131], v[148:149], 2, s[44:45]
	global_store_dword v[130:131], v129, off
